# combine gate GEMV moved to v_mfma_f32_16x16x4_f32 (f32 operands), result transposed through LDS
# speedup vs baseline: 1.0078x; 1.0031x over previous
; __device__ void phase_combine(const P& p, int l, int ntok, float* lds) {
;     ...
;   const float* g2 = p.rw_g2 + (size_t)l * 96 * 512;
;   float g2r[96];
; #pragma unroll
;   for (int m = 0; m < 96; ++m) g2r[m] = g2[m * 512 + tid];
.LBB0_87:
	s_andn2_b64 vcc, exec, s[0:1]
	s_cbranch_vccnz .LBB0_96
	s_lshr_b32 s72, s56, 4
	v_readlane_b32 s0, v240, 0
	s_cmp_ge_i32 s0, s72
	s_waitcnt vmcnt(0)
	v_mov_b32_e32 v4, v168
	s_cbranch_scc1 .LBB0_96
	s_mul_i32 s0, s64, 0x30000
	v_readlane_b32 s36, v238, 22
	s_mul_hi_i32 s1, s64, 0x30000
	v_readlane_b32 s37, v238, 23
	s_add_u32 s0, s36, s0
	v_ashrrev_i32_e32 v5, 31, v4
	s_addc_u32 s1, s37, s1
	v_lshlrev_b64 v[32:33], 2, v[4:5]
	v_lshl_add_u64 v[0:1], s[0:1], 0, v[32:33]
	v_add_co_u32_e32 v2, vcc, s96, v0
	s_movk_i32 s0, 0x4000
	s_nop 0
	v_addc_co_u32_e32 v3, vcc, 0, v1, vcc
	v_add_co_u32_e32 v8, vcc, s78, v0
	s_mul_hi_i32 s1, s64, 0x3000
	s_nop 0
	v_addc_co_u32_e32 v9, vcc, 0, v1, vcc
	v_add_co_u32_e32 v6, vcc, s75, v0
	s_mov_b64 s[2:3], s[64:65]
	s_nop 0
	v_addc_co_u32_e32 v7, vcc, 0, v1, vcc
	v_add_co_u32_e32 v12, vcc, s0, v0
	s_movk_i32 s0, 0x5000
	s_nop 0
	v_addc_co_u32_e32 v13, vcc, 0, v1, vcc
	v_add_co_u32_e32 v10, vcc, s0, v0
	s_movk_i32 s0, 0x6000
	s_nop 0
	v_addc_co_u32_e32 v11, vcc, 0, v1, vcc
	v_add_co_u32_e32 v16, vcc, s0, v0
	s_movk_i32 s0, 0x7000
	s_nop 0
	v_addc_co_u32_e32 v17, vcc, 0, v1, vcc
	v_add_co_u32_e32 v14, vcc, s0, v0
	s_mov_b32 s0, 0x8000
	s_nop 0
	v_addc_co_u32_e32 v15, vcc, 0, v1, vcc
	v_add_co_u32_e32 v22, vcc, s0, v0
	s_mov_b32 s0, 0x9000
	s_nop 0
	v_addc_co_u32_e32 v23, vcc, 0, v1, vcc
	v_add_co_u32_e32 v18, vcc, s0, v0
	s_mov_b32 s0, 0xa000
	s_nop 0
	v_addc_co_u32_e32 v19, vcc, 0, v1, vcc
	v_add_co_u32_e32 v26, vcc, s0, v0
	s_mov_b32 s0, 0xb000
	s_nop 0
	v_addc_co_u32_e32 v27, vcc, 0, v1, vcc
	v_add_co_u32_e32 v24, vcc, s0, v0
	s_mov_b32 s0, 0xc000
	s_nop 0
	v_addc_co_u32_e32 v25, vcc, 0, v1, vcc
	v_add_co_u32_e32 v30, vcc, s0, v0
	s_mov_b32 s0, 0xd000
	s_nop 0
	v_addc_co_u32_e32 v31, vcc, 0, v1, vcc
	v_add_co_u32_e32 v20, vcc, s0, v0
	s_mov_b32 s0, 0xe000
	s_nop 0
	v_addc_co_u32_e32 v21, vcc, 0, v1, vcc
	v_add_co_u32_e32 v34, vcc, s0, v0
	s_mov_b32 s0, 0xf000
	s_nop 0
	v_addc_co_u32_e32 v35, vcc, 0, v1, vcc
	v_add_co_u32_e32 v28, vcc, s0, v0
	s_mov_b32 s0, 0x10000
	s_nop 0
	v_addc_co_u32_e32 v29, vcc, 0, v1, vcc
	v_add_co_u32_e32 v38, vcc, s0, v0
	s_mov_b32 s0, 0x11000
	s_nop 0
	v_addc_co_u32_e32 v39, vcc, 0, v1, vcc
	v_add_co_u32_e32 v36, vcc, s0, v0
	s_mov_b32 s0, 0x12000
	s_nop 0
	v_addc_co_u32_e32 v37, vcc, 0, v1, vcc
	v_add_co_u32_e32 v42, vcc, s0, v0
	s_mov_b32 s0, 0x13000
	s_nop 0
	v_addc_co_u32_e32 v43, vcc, 0, v1, vcc
	v_add_co_u32_e32 v40, vcc, s0, v0
	s_mov_b32 s0, 0x14000
	s_nop 0
	v_addc_co_u32_e32 v41, vcc, 0, v1, vcc
	v_add_co_u32_e32 v46, vcc, s0, v0
	s_mov_b32 s0, 0x15000
	s_nop 0
	v_addc_co_u32_e32 v47, vcc, 0, v1, vcc
	v_add_co_u32_e32 v44, vcc, s0, v0
	s_mov_b32 s0, 0x16000
	s_nop 0
	v_addc_co_u32_e32 v45, vcc, 0, v1, vcc
	v_add_co_u32_e32 v50, vcc, s0, v0
	s_mov_b32 s0, 0x17000
	s_nop 0
	v_addc_co_u32_e32 v51, vcc, 0, v1, vcc
	v_add_co_u32_e32 v48, vcc, s0, v0
	s_mov_b32 s0, 0x18000
	s_nop 0
	v_addc_co_u32_e32 v49, vcc, 0, v1, vcc
	v_add_co_u32_e32 v56, vcc, s0, v0
	s_mov_b32 s0, 0x19000
	s_nop 0
	v_addc_co_u32_e32 v57, vcc, 0, v1, vcc
	v_add_co_u32_e32 v52, vcc, s0, v0
	s_mov_b32 s0, 0x1a000
	s_nop 0
	v_addc_co_u32_e32 v53, vcc, 0, v1, vcc
	v_add_co_u32_e32 v60, vcc, s0, v0
	s_mov_b32 s0, 0x1b000
	s_nop 0
	v_addc_co_u32_e32 v61, vcc, 0, v1, vcc
	v_add_co_u32_e32 v58, vcc, s0, v0
	s_mov_b32 s0, 0x1c000
	s_nop 0
	v_addc_co_u32_e32 v59, vcc, 0, v1, vcc
	v_add_co_u32_e32 v64, vcc, s0, v0
	s_mov_b32 s0, 0x1d000
	s_nop 0
	v_addc_co_u32_e32 v65, vcc, 0, v1, vcc
	v_add_co_u32_e32 v54, vcc, s0, v0
	s_mov_b32 s0, 0x1e000
	s_nop 0
	v_addc_co_u32_e32 v55, vcc, 0, v1, vcc
	v_add_co_u32_e32 v66, vcc, s0, v0
	s_mov_b32 s0, 0x1f000
	s_nop 0
	v_addc_co_u32_e32 v67, vcc, 0, v1, vcc
	v_add_co_u32_e32 v62, vcc, s0, v0
	s_mov_b32 s0, 0x20000
	s_nop 0
	v_addc_co_u32_e32 v63, vcc, 0, v1, vcc
	v_add_co_u32_e32 v70, vcc, s0, v0
	s_mov_b32 s0, 0x21000
	s_nop 0
	v_addc_co_u32_e32 v71, vcc, 0, v1, vcc
	v_add_co_u32_e32 v68, vcc, s0, v0
	s_mov_b32 s0, 0x22000
	s_nop 0
	v_addc_co_u32_e32 v69, vcc, 0, v1, vcc
	v_add_co_u32_e32 v74, vcc, s0, v0
	s_mov_b32 s0, 0x23000
	s_nop 0
	v_addc_co_u32_e32 v75, vcc, 0, v1, vcc
	v_add_co_u32_e32 v72, vcc, s0, v0
	s_mov_b32 s0, 0x24000
	s_nop 0
	v_addc_co_u32_e32 v73, vcc, 0, v1, vcc
	v_add_co_u32_e32 v104, vcc, s0, v0
	s_mov_b32 s0, 0x25000
	s_nop 0
	v_addc_co_u32_e32 v105, vcc, 0, v1, vcc
	v_add_co_u32_e32 v76, vcc, s0, v0
	s_mov_b32 s0, 0x26000
	s_nop 0
	v_addc_co_u32_e32 v77, vcc, 0, v1, vcc
	v_add_co_u32_e32 v106, vcc, s0, v0
	s_mov_b32 s0, 0x27000
	s_nop 0
	v_addc_co_u32_e32 v107, vcc, 0, v1, vcc
	v_add_co_u32_e32 v114, vcc, s0, v0
	s_mov_b32 s0, 0x28000
	s_nop 0
	v_addc_co_u32_e32 v115, vcc, 0, v1, vcc
	v_add_co_u32_e32 v108, vcc, s0, v0
	s_mov_b32 s0, 0x29000
	s_nop 0
	v_addc_co_u32_e32 v109, vcc, 0, v1, vcc
	v_add_co_u32_e32 v116, vcc, s0, v0
	s_mov_b32 s0, 0x2a000
	s_nop 0
	v_addc_co_u32_e32 v117, vcc, 0, v1, vcc
	v_add_co_u32_e32 v112, vcc, s0, v0
	s_mov_b32 s0, 0x2b000
	s_nop 0
	v_addc_co_u32_e32 v113, vcc, 0, v1, vcc
	v_add_co_u32_e32 v118, vcc, s0, v0
	s_mov_b32 s0, 0x2c000
	s_nop 0
	v_addc_co_u32_e32 v119, vcc, 0, v1, vcc
	v_add_co_u32_e32 v120, vcc, s0, v0
	s_mov_b32 s0, 0x2d000
	s_nop 0
	v_addc_co_u32_e32 v121, vcc, 0, v1, vcc
	v_add_co_u32_e32 v122, vcc, s0, v0
	s_mov_b32 s0, 0x2e000
	s_nop 0
	v_addc_co_u32_e32 v123, vcc, 0, v1, vcc
	v_add_co_u32_e32 v124, vcc, s0, v0
	s_mov_b32 s0, 0x2f000
	s_nop 0
	v_addc_co_u32_e32 v125, vcc, 0, v1, vcc
	v_add_co_u32_e32 v126, vcc, s0, v0
	s_mul_i32 s0, s64, 0x3000
	v_readlane_b32 s52, v238, 6
	v_readlane_b32 s56, v238, 10
	v_readlane_b32 s57, v238, 11
	s_add_u32 s0, s56, s0
	v_readlane_b32 s64, v238, 18
; __device__ void phase_combine(const P& p, int l, int ntok, float* lds) {
;     ...
;   const float* g2 = p.rw_g2 + (size_t)l * 96 * 512;
;   float g2r[96];
; #pragma unroll
;   for (int m = 0; m < 96; ++m) g2r[m] = g2[m * 512 + tid];
;   const float gnw = p.rw_gn_w[(size_t)l * 512 + tid], gnb = p.rw_gn_b[(size_t)l * 512 + tid];
;   const float muvf = p.rw_mu_rkv[((size_t)l * 2 + 0) * 1536 + 1024 + tid];
;   const float muvb = p.rw_mu_rkv[((size_t)l * 2 + 1) * 1536 + 1024 + tid];
;   const float scw0 = p.sc_conv[(size_t)l * 1536 + tid], scw1 = p.sc_conv[(size_t)l * 1536 + 512 + tid],
;               scw2 = p.sc_conv[(size_t)l * 1536 + 1024 + tid];
	v_readlane_b32 s65, v238, 19
	s_addc_u32 s1, s57, s1
	v_addc_co_u32_e32 v127, vcc, 0, v1, vcc
	s_mov_b64 s[64:65], s[2:3]
	v_lshl_add_u64 v[78:79], s[0:1], 0, v[32:33]
	v_readlane_b32 s54, v238, 8
	v_add_co_u32_e32 v134, vcc, s96, v78
	s_mul_i32 s0, s64, 0x1800
	v_readlane_b32 s55, v238, 9
	v_addc_co_u32_e32 v135, vcc, 0, v79, vcc
	s_mul_hi_i32 s1, s64, 0x1800
	s_add_u32 s0, s54, s0
	v_add_co_u32_e32 v136, vcc, s78, v78
	s_addc_u32 s1, s55, s1
	v_readlane_b32 s38, v238, 24
	v_readlane_b32 s39, v238, 25
	v_readlane_b32 s40, v238, 26
	v_readlane_b32 s41, v238, 27
	v_readlane_b32 s42, v238, 28
	v_readlane_b32 s43, v238, 29
	v_readlane_b32 s44, v238, 30
	v_readlane_b32 s45, v238, 31
	v_readlane_b32 s46, v238, 32
	v_readlane_b32 s47, v238, 33
	v_readlane_b32 s48, v238, 34
	v_readlane_b32 s49, v238, 35
	v_readlane_b32 s50, v238, 36
	v_readlane_b32 s51, v238, 37
	v_addc_co_u32_e32 v137, vcc, 0, v79, vcc
	v_lshl_add_u64 v[138:139], s[0:1], 0, v[32:33]
	v_add_co_u32_e32 v140, vcc, s96, v138
	v_readlane_b32 s36, v239, 54
	v_readlane_b32 s53, v238, 7
	v_addc_co_u32_e32 v141, vcc, 0, v139, vcc
	v_readlane_b32 s45, v239, 63
	s_movk_i32 s0, 0x100
	v_mov_b32_e32 v32, s53
	v_readlane_b32 s44, v239, 62
	v_mov_b32_e32 v33, s45
	v_cmp_gt_u32_e32 vcc, s0, v4
	v_readlane_b32 s0, v238, 47
	v_readlane_b32 s37, v239, 55
	v_cndmask_b32_e32 v143, v32, v33, vcc
	v_mov_b32_e32 v32, s52
	v_mov_b32_e32 v33, s44
	v_cndmask_b32_e32 v142, v32, v33, vcc
	s_nop 0
	s_nop 0
	s_nop 0
	s_nop 0
	s_nop 0
	s_nop 0
	s_nop 0
	s_nop 0
	s_nop 0
	s_nop 0
	s_nop 0
	s_nop 0
	s_nop 0
	s_nop 0
	s_nop 0
	s_nop 0
	s_nop 0
	s_nop 0
	s_nop 0
	s_nop 0
	s_nop 0
	s_nop 0
	s_nop 0
	s_nop 0
	s_nop 0
	s_nop 0
	s_nop 0
	s_nop 0
	s_nop 0
	s_nop 0
	s_nop 0
	s_nop 0
	s_nop 0
	s_nop 0
	s_nop 0
	s_nop 0
	s_nop 0
	s_nop 0
	s_nop 0
	v_bfe_u32 v246, v168, 4, 2
	v_mul_u32_u24_e32 v246, 0x7c0, v246
	v_add_u32_e32 v246, 0xfffd1000, v246
	v_mov_b32_e32 v247, -1
	v_mov_b32_e32 v250, 0x2000
	v_mov_b32_e32 v251, 0
	v_lshl_add_u64 v[244:245], v[126:127], 0, v[246:247]
	global_load_dword v90, v[244:245], off
	global_load_dword v91, v[244:245], off offset:64
	global_load_dword v32, v[244:245], off offset:128
	global_load_dword v92, v[244:245], off offset:192
	v_lshl_add_u64 v[244:245], v[244:245], 0, v[250:251]
	global_load_dword v33, v[244:245], off
	global_load_dword v78, v[244:245], off offset:64
	global_load_dword v79, v[244:245], off offset:128
	global_load_dword v93, v[244:245], off offset:192
	v_lshl_add_u64 v[244:245], v[244:245], 0, v[250:251]
	global_load_dword v80, v[244:245], off
	global_load_dword v81, v[244:245], off offset:64
	global_load_dword v82, v[244:245], off offset:128
	global_load_dword v11, v[244:245], off offset:192
	v_lshl_add_u64 v[244:245], v[244:245], 0, v[250:251]
	global_load_dword v83, v[244:245], off
	global_load_dword v84, v[244:245], off offset:64
	global_load_dword v85, v[244:245], off offset:128
	global_load_dword v94, v[244:245], off offset:192
	v_lshl_add_u64 v[244:245], v[244:245], 0, v[250:251]
	global_load_dword v86, v[244:245], off
	global_load_dword v87, v[244:245], off offset:64
	global_load_dword v88, v[244:245], off offset:128
	global_load_dword v95, v[244:245], off offset:192
	v_lshl_add_u64 v[244:245], v[244:245], 0, v[250:251]
	global_load_dword v89, v[244:245], off
	global_load_dword v26, v[244:245], off offset:64
	global_load_dword v27, v[244:245], off offset:128
	global_load_dword v24, v[244:245], off offset:192
	v_lshl_add_u64 v[244:245], v[244:245], 0, v[250:251]
	global_load_dword v25, v[244:245], off
	global_load_dword v30, v[244:245], off offset:64
	global_load_dword v31, v[244:245], off offset:128
	global_load_dword v103, v[244:245], off offset:192
	v_lshl_add_u64 v[244:245], v[244:245], 0, v[250:251]
	global_load_dword v96, v[244:245], off
	global_load_dword v34, v[244:245], off offset:64
	global_load_dword v35, v[244:245], off offset:128
	global_load_dword v28, v[244:245], off offset:192
	v_lshl_add_u64 v[244:245], v[244:245], 0, v[250:251]
	global_load_dword v97, v[244:245], off
	global_load_dword v38, v[244:245], off offset:64
	global_load_dword v39, v[244:245], off offset:128
	global_load_dword v29, v[244:245], off offset:192
	v_lshl_add_u64 v[244:245], v[244:245], 0, v[250:251]
	global_load_dword v98, v[244:245], off
	global_load_dword v42, v[244:245], off offset:64
	global_load_dword v43, v[244:245], off offset:128
	global_load_dword v36, v[244:245], off offset:192
	v_lshl_add_u64 v[244:245], v[244:245], 0, v[250:251]
	global_load_dword v99, v[244:245], off
	global_load_dword v46, v[244:245], off offset:64
	global_load_dword v47, v[244:245], off offset:128
	global_load_dword v37, v[244:245], off offset:192
	v_lshl_add_u64 v[244:245], v[244:245], 0, v[250:251]
	global_load_dword v100, v[244:245], off
	global_load_dword v50, v[244:245], off offset:64
	global_load_dword v51, v[244:245], off offset:128
	global_load_dword v40, v[244:245], off offset:192
	v_lshl_add_u64 v[244:245], v[244:245], 0, v[250:251]
	global_load_dword v101, v[244:245], off
	global_load_dword v56, v[244:245], off offset:64
	global_load_dword v57, v[244:245], off offset:128
	global_load_dword v41, v[244:245], off offset:192
	v_lshl_add_u64 v[244:245], v[244:245], 0, v[250:251]
	global_load_dword v102, v[244:245], off
	global_load_dword v60, v[244:245], off offset:64
; __device__ void phase_combine(const P& p, int l, int ntok, float* lds) {
;     ...
;   const float* g2 = p.rw_g2 + (size_t)l * 96 * 512;
;   float g2r[96];
; #pragma unroll
;   for (int m = 0; m < 96; ++m) g2r[m] = g2[m * 512 + tid];
;   const float gnw = p.rw_gn_w[(size_t)l * 512 + tid], gnb = p.rw_gn_b[(size_t)l * 512 + tid];
;   const float muvf = p.rw_mu_rkv[((size_t)l * 2 + 0) * 1536 + 1024 + tid];
;   const float muvb = p.rw_mu_rkv[((size_t)l * 2 + 1) * 1536 + 1024 + tid];
;   const float scw0 = p.sc_conv[(size_t)l * 1536 + tid], scw1 = p.sc_conv[(size_t)l * 1536 + 512 + tid],
;               scw2 = p.sc_conv[(size_t)l * 1536 + 1024 + tid];
;   const int mixer = wv >> 2, hh = wv & 3;
;   const float* ng = (mixer == 0 ? p.gla_norm_g : p.gdn_norm_g) + (size_t)l * 128;
;   const float ng0 = ng[lane], ng1 = ng[lane + 64];
;   const u16* om0 = osc_ptr(p, mixer, 0);
;   const u16* om1 = osc_ptr(p, mixer, 1);
;   const u16* or0 = osc_ptr(p, 2, 0);
;   const u16* or1 = osc_ptr(p, 2, 1);
;   const int gch = (mixer == 0 ? O_GR : O_DZ) + hh * 128 + lane;
	global_load_dword v61, v[244:245], off offset:128
	global_load_dword v44, v[244:245], off offset:192
	v_lshl_add_u64 v[244:245], v[244:245], 0, v[250:251]
	global_load_dword v45, v[244:245], off
	global_load_dword v48, v[244:245], off offset:64
	global_load_dword v49, v[244:245], off offset:128
	global_load_dword v54, v[244:245], off offset:192
	v_lshl_add_u64 v[244:245], v[244:245], 0, v[250:251]
	global_load_dword v52, v[244:245], off
	global_load_dword v53, v[244:245], off offset:64
	global_load_dword v58, v[244:245], off offset:128
	global_load_dword v55, v[244:245], off offset:192
	v_lshl_add_u64 v[244:245], v[244:245], 0, v[250:251]
	global_load_dword v59, v[244:245], off
	global_load_dword v64, v[244:245], off offset:64
	global_load_dword v65, v[244:245], off offset:128
	global_load_dword v62, v[244:245], off offset:192
	v_lshl_add_u64 v[244:245], v[244:245], 0, v[250:251]
	global_load_dword v66, v[244:245], off
	global_load_dword v67, v[244:245], off offset:64
	global_load_dword v70, v[244:245], off offset:128
	global_load_dword v63, v[244:245], off offset:192
	v_lshl_add_u64 v[244:245], v[244:245], 0, v[250:251]
	global_load_dword v71, v[244:245], off
	global_load_dword v74, v[244:245], off offset:64
	global_load_dword v75, v[244:245], off offset:128
	global_load_dword v68, v[244:245], off offset:192
	v_lshl_add_u64 v[244:245], v[244:245], 0, v[250:251]
	global_load_dword v104, v[244:245], off
	global_load_dword v105, v[244:245], off offset:64
	global_load_dword v106, v[244:245], off offset:128
	global_load_dword v69, v[244:245], off offset:192
	v_lshl_add_u64 v[244:245], v[244:245], 0, v[250:251]
	global_load_dword v107, v[244:245], off
	global_load_dword v108, v[244:245], off offset:64
	global_load_dword v109, v[244:245], off offset:128
	global_load_dword v72, v[244:245], off offset:192
	v_lshl_add_u64 v[244:245], v[244:245], 0, v[250:251]
	global_load_dword v110, v[244:245], off
	global_load_dword v111, v[244:245], off offset:64
	global_load_dword v112, v[244:245], off offset:128
	global_load_dword v73, v[244:245], off offset:192
	v_lshl_add_u64 v[244:245], v[244:245], 0, v[250:251]
	global_load_dword v76, v[244:245], off
	global_load_dword v77, v[244:245], off offset:64
	global_load_dword v113, v[244:245], off offset:128
	global_load_dword v116, v[244:245], off offset:192
	v_lshl_add_u64 v[244:245], v[244:245], 0, v[250:251]
	global_load_dword v114, v[244:245], off
	global_load_dword v115, v[244:245], off offset:64
	global_load_dword v117, v[244:245], off offset:128
	global_load_dword v118, v[244:245], off offset:192
	v_readlane_b32 s38, v239, 56
	v_readlane_b32 s39, v239, 57
	v_readlane_b32 s40, v239, 58
	v_readlane_b32 s41, v239, 59
	v_readlane_b32 s42, v239, 60
	v_readlane_b32 s43, v239, 61
	v_readlane_b32 s46, v238, 0
	v_readlane_b32 s47, v238, 1
	v_readlane_b32 s48, v238, 2
	v_readlane_b32 s49, v238, 3
	v_readlane_b32 s50, v238, 4
	v_readlane_b32 s51, v238, 5
	v_readlane_b32 s1, v238, 48
	v_readlane_b32 s36, v238, 22
	v_readlane_b32 s44, v238, 30
	v_lshl_add_u64 v[0:1], s[0:1], 0, v[4:5]
	v_lshlrev_b64 v[0:1], 2, v[0:1]
	v_readlane_b32 s45, v238, 31
	v_readlane_b32 s46, v238, 32
	v_readlane_b32 s47, v238, 33
	v_lshl_add_u64 v[2:3], s[44:45], 0, v[0:1]
	global_load_dword v119, v[2:3], off
	v_lshl_add_u64 v[0:1], s[46:47], 0, v[0:1]
	global_load_dword v120, v[0:1], off
	global_load_dword v121, v[134:135], off
	global_load_dword v122, v[136:137], off offset:2048
	global_load_dword v123, v[138:139], off
	global_load_dword v124, v[138:139], off offset:2048
	global_load_dword v125, v[140:141], off
	v_and_b32_e32 v145, 63, v4
	v_lshl_add_u64 v[0:1], v[142:143], 0, s[0:1]
	v_lshlrev_b32_e32 v128, 2, v145
	v_lshl_add_u64 v[0:1], v[0:1], 0, v[128:129]
	global_load_dword v126, v[0:1], off
	global_load_dword v127, v[0:1], off offset:256
	v_ashrrev_i32_e32 v3, 8, v4
	v_lshlrev_b32_e32 v2, 1, v3
	v_mov_b64_e32 v[0:1], s[8:9]
	s_mov_b32 s2, 0x1100000
	v_mad_i64_i32 v[6:7], s[0:1], v2, s2, v[0:1]
	v_or_b32_e32 v2, 1, v2
	v_mad_i64_i32 v[8:9], s[0:1], v2, s2, v[0:1]
	v_ashrrev_i32_e32 v0, 6, v4
	v_lshlrev_b32_e32 v2, 7, v0
	v_lshlrev_b32_e32 v12, 9, v3
	v_cndmask_b32_e32 v144, v177, v178, vcc
	v_and_b32_e32 v14, 0x180, v2
	v_ashrrev_i32_e32 v13, 31, v12
	v_add_u32_e32 v1, v144, v145
	v_lshl_add_u64 v[12:13], v[12:13], 1, s[92:93]
	v_lshlrev_b32_e32 v128, 1, v14
	v_readlane_b32 s38, v238, 24
	v_readlane_b32 s39, v238, 25
	v_or_b32_e32 v2, v1, v14
	v_ashrrev_i32_e32 v1, 31, v0
	v_lshl_add_u64 v[12:13], v[12:13], 0, v[128:129]
	v_lshlrev_b32_e32 v128, 1, v145
	s_movk_i32 s0, 0x600
	v_or_b32_e32 v10, v14, v145
	v_lshl_add_u64 v[12:13], v[12:13], 0, v[128:129]
	v_lshl_add_u64 v[14:15], v[4:5], 1, s[92:93]
	v_lshl_add_u32 v128, v4, 2, 0
	v_lshlrev_b64 v[16:17], 2, v[0:1]
	v_lshlrev_b32_e32 v134, 1, v2
	v_readlane_b32 s55, v240, 0
	v_cmp_gt_i32_e64 s[38:39], s0, v4
	v_readlane_b32 s58, v238, 12
	v_readlane_b32 s59, v238, 13
	v_readlane_b32 s60, v238, 14
	v_readlane_b32 s61, v238, 15
	v_readlane_b32 s62, v238, 16
	v_readlane_b32 s63, v238, 17
	v_readlane_b32 s66, v238, 20
	v_readlane_b32 s67, v238, 21
	v_readlane_b32 s37, v238, 23
	v_readlane_b32 s40, v238, 26
	v_readlane_b32 s41, v238, 27
	v_readlane_b32 s42, v238, 28
	v_readlane_b32 s43, v238, 29
	v_readlane_b32 s48, v238, 34
	v_readlane_b32 s49, v238, 35
	v_readlane_b32 s50, v238, 36
	v_readlane_b32 s51, v238, 37

; __device__ void phase_combine(const P& p, int l, int ntok, float* lds) {
;     ...
;         for (int m = 0; m < 96; m += 4) {
; #pragma unroll
;           for (int i = 0; i < 4; ++i) {
;             float4 s = *reinterpret_cast<const float4*>(sig + (i0 + i) * 96 + m);
;             gate[i] += s.x * g2r[m] + s.y * g2r[m + 1] + s.z * g2r[m + 2] + s.w * g2r[m + 3];
;           }
;         }
.LBB0_93:
	s_or_b64 exec, exec, s[0:1]
	s_cmpk_lt_i32 s55, 0x400
	s_movk_i32 s0, 0xfff
	s_cselect_b32 s57, s0, 0xff
	v_readlane_b32 s34, v240, 12
	v_readlane_b32 s62, v240, 14
	s_cselect_b32 s58, 63, 0xff
	s_and_b32 s59, s57, s56
	s_mov_b32 s60, 0
	v_readlane_b32 s35, v240, 13
	v_readlane_b32 s63, v240, 15
	s_mov_b32 s33, 0x800000
	s_movk_i32 s61, 0x3600
	s_mov_b32 s66, 0x88000
	s_mov_b64 s[68:69], 0x3040
	s_waitcnt lgkmcnt(0)
	s_barrier
	v_and_b32_e32 v244, 15, v168
	v_bfe_u32 v245, v168, 4, 2
	v_mul_u32_u24_e32 v244, 0x180, v244
	v_mul_u32_u24_e32 v246, 0x1fc0, v245
	v_lshl_add_u32 v244, v245, 2, v244
	v_lshl_add_u32 v246, v168, 2, v246
	ds_read_b32 v190, v244
	ds_read_b32 v191, v244 offset:16
	ds_read_b32 v192, v244 offset:32
	ds_read_b32 v193, v244 offset:48
	ds_read_b32 v194, v244 offset:64
	ds_read_b32 v195, v244 offset:80
	ds_read_b32 v196, v244 offset:96
	ds_read_b32 v197, v244 offset:112
	ds_read_b32 v198, v244 offset:128
	ds_read_b32 v199, v244 offset:144
	ds_read_b32 v200, v244 offset:160
	ds_read_b32 v201, v244 offset:176
	s_waitcnt lgkmcnt(4)
	ds_read_b32 v202, v244 offset:192
	ds_read_b32 v203, v244 offset:208
	ds_read_b32 v204, v244 offset:224
	ds_read_b32 v205, v244 offset:240
	ds_read_b32 v206, v244 offset:256
	ds_read_b32 v207, v244 offset:272
	ds_read_b32 v208, v244 offset:288
	ds_read_b32 v209, v244 offset:304
	ds_read_b32 v210, v244 offset:320
	ds_read_b32 v211, v244 offset:336
	ds_read_b32 v212, v244 offset:352
	ds_read_b32 v213, v244 offset:368
	s_waitcnt lgkmcnt(0)
	v_mfma_f32_16x16x4_f32 v[220:223], v190, v90, 0
	v_mfma_f32_16x16x4_f32 v[220:223], v191, v33, v[220:223]
	v_mfma_f32_16x16x4_f32 v[220:223], v192, v80, v[220:223]
	v_mfma_f32_16x16x4_f32 v[220:223], v193, v83, v[220:223]
	v_mfma_f32_16x16x4_f32 v[220:223], v194, v86, v[220:223]
	v_mfma_f32_16x16x4_f32 v[220:223], v195, v89, v[220:223]
	v_mfma_f32_16x16x4_f32 v[220:223], v196, v25, v[220:223]
	v_mfma_f32_16x16x4_f32 v[220:223], v197, v96, v[220:223]
	v_mfma_f32_16x16x4_f32 v[220:223], v198, v97, v[220:223]
	v_mfma_f32_16x16x4_f32 v[220:223], v199, v98, v[220:223]
	v_mfma_f32_16x16x4_f32 v[220:223], v200, v99, v[220:223]
	v_mfma_f32_16x16x4_f32 v[220:223], v201, v100, v[220:223]
	v_mfma_f32_16x16x4_f32 v[220:223], v202, v101, v[220:223]
	v_mfma_f32_16x16x4_f32 v[220:223], v203, v102, v[220:223]
	v_mfma_f32_16x16x4_f32 v[220:223], v204, v45, v[220:223]
	v_mfma_f32_16x16x4_f32 v[220:223], v205, v52, v[220:223]
	v_mfma_f32_16x16x4_f32 v[220:223], v206, v59, v[220:223]
	v_mfma_f32_16x16x4_f32 v[220:223], v207, v66, v[220:223]
	v_mfma_f32_16x16x4_f32 v[220:223], v208, v71, v[220:223]
	v_mfma_f32_16x16x4_f32 v[220:223], v209, v104, v[220:223]
	v_mfma_f32_16x16x4_f32 v[220:223], v210, v107, v[220:223]
	v_mfma_f32_16x16x4_f32 v[220:223], v211, v110, v[220:223]
	v_mfma_f32_16x16x4_f32 v[220:223], v212, v76, v[220:223]
	v_mfma_f32_16x16x4_f32 v[220:223], v213, v114, v[220:223]
	v_mfma_f32_16x16x4_f32 v[224:227], v190, v91, 0
	v_mfma_f32_16x16x4_f32 v[224:227], v191, v78, v[224:227]
	v_mfma_f32_16x16x4_f32 v[224:227], v192, v81, v[224:227]
	v_mfma_f32_16x16x4_f32 v[224:227], v193, v84, v[224:227]
	v_mfma_f32_16x16x4_f32 v[224:227], v194, v87, v[224:227]
	v_mfma_f32_16x16x4_f32 v[224:227], v195, v26, v[224:227]
	v_mfma_f32_16x16x4_f32 v[224:227], v196, v30, v[224:227]
	v_mfma_f32_16x16x4_f32 v[224:227], v197, v34, v[224:227]
	v_mfma_f32_16x16x4_f32 v[224:227], v198, v38, v[224:227]
	v_mfma_f32_16x16x4_f32 v[224:227], v199, v42, v[224:227]
	v_mfma_f32_16x16x4_f32 v[224:227], v200, v46, v[224:227]
	v_mfma_f32_16x16x4_f32 v[224:227], v201, v50, v[224:227]
	v_mfma_f32_16x16x4_f32 v[224:227], v202, v56, v[224:227]
	v_mfma_f32_16x16x4_f32 v[224:227], v203, v60, v[224:227]
	v_mfma_f32_16x16x4_f32 v[224:227], v204, v48, v[224:227]
	v_mfma_f32_16x16x4_f32 v[224:227], v205, v53, v[224:227]
	v_mfma_f32_16x16x4_f32 v[224:227], v206, v64, v[224:227]
	v_mfma_f32_16x16x4_f32 v[224:227], v207, v67, v[224:227]
	v_mfma_f32_16x16x4_f32 v[224:227], v208, v74, v[224:227]
	v_mfma_f32_16x16x4_f32 v[224:227], v209, v105, v[224:227]
	v_mfma_f32_16x16x4_f32 v[224:227], v210, v108, v[224:227]
	v_mfma_f32_16x16x4_f32 v[224:227], v211, v111, v[224:227]
	v_mfma_f32_16x16x4_f32 v[224:227], v212, v77, v[224:227]
	v_mfma_f32_16x16x4_f32 v[224:227], v213, v115, v[224:227]
	v_mfma_f32_16x16x4_f32 v[228:231], v190, v32, 0
	v_mfma_f32_16x16x4_f32 v[228:231], v191, v79, v[228:231]
	v_mfma_f32_16x16x4_f32 v[228:231], v192, v82, v[228:231]
	v_mfma_f32_16x16x4_f32 v[228:231], v193, v85, v[228:231]
	v_mfma_f32_16x16x4_f32 v[228:231], v194, v88, v[228:231]
	v_mfma_f32_16x16x4_f32 v[228:231], v195, v27, v[228:231]
	v_mfma_f32_16x16x4_f32 v[228:231], v196, v31, v[228:231]
	v_mfma_f32_16x16x4_f32 v[228:231], v197, v35, v[228:231]
	v_mfma_f32_16x16x4_f32 v[228:231], v198, v39, v[228:231]
	v_mfma_f32_16x16x4_f32 v[228:231], v199, v43, v[228:231]
	v_mfma_f32_16x16x4_f32 v[228:231], v200, v47, v[228:231]
	v_mfma_f32_16x16x4_f32 v[228:231], v201, v51, v[228:231]
	v_mfma_f32_16x16x4_f32 v[228:231], v202, v57, v[228:231]
	v_mfma_f32_16x16x4_f32 v[228:231], v203, v61, v[228:231]
	v_mfma_f32_16x16x4_f32 v[228:231], v204, v49, v[228:231]
	v_mfma_f32_16x16x4_f32 v[228:231], v205, v58, v[228:231]
	v_mfma_f32_16x16x4_f32 v[228:231], v206, v65, v[228:231]
	v_mfma_f32_16x16x4_f32 v[228:231], v207, v70, v[228:231]
	v_mfma_f32_16x16x4_f32 v[228:231], v208, v75, v[228:231]
	v_mfma_f32_16x16x4_f32 v[228:231], v209, v106, v[228:231]
	v_mfma_f32_16x16x4_f32 v[228:231], v210, v109, v[228:231]
	v_mfma_f32_16x16x4_f32 v[228:231], v211, v112, v[228:231]
	v_mfma_f32_16x16x4_f32 v[228:231], v212, v113, v[228:231]
; __device__ void phase_combine(const P& p, int l, int ntok, float* lds) {
;     ...
;       for (int i = 0; i < 4; ++i) {
;         int row = r0 + i0 + i, t = tb + i0 + i;
;         y0[i] = or0[(size_t)row * 512 + tid]; y1[i] = or1[(size_t)row * 512 + tid];
;         const u16* pv = p.projb + (size_t)row * PROJP + O_RKV + 1024 + tid;
;         vc[i] = pv[0]; vp[i] = pv[t > 0 ? -PROJP : 0]; vn[i] = pv[t < T - 1 ? PROJP : 0];
;         sf[i] = p.sbon[(size_t)row * 8 + wv]; sb[i] = p.sbon[(size_t)NT * 8 + (size_t)row * 8 + wv];
;         size_t ob = (size_t)row * 512 + hh * 128 + lane;
;         a0[i] = om0[ob]; a1[i] = om1[ob]; a2[i] = om0[ob + 64]; a3[i] = om1[ob + 64];
;         const u16* pg = p.projb + (size_t)row * PROJP + gch;
;         g0r[i] = pg[0]; g1r[i] = pg[64];
;         cbr[i] = p.projb[(size_t)row * PROJP + O_CB + tid];
;       }
;     ...
;         for (int m = 0; m < 96; m += 4) {
; #pragma unroll
;           for (int i = 0; i < 4; ++i) {
;             float4 s = *reinterpret_cast<const float4*>(sig + (i0 + i) * 96 + m);
;             gate[i] += s.x * g2r[m] + s.y * g2r[m + 1] + s.z * g2r[m + 2] + s.w * g2r[m + 3];
;           }
;         }
	v_mfma_f32_16x16x4_f32 v[228:231], v213, v117, v[228:231]
	v_mfma_f32_16x16x4_f32 v[232:235], v190, v92, 0
	v_mfma_f32_16x16x4_f32 v[232:235], v191, v93, v[232:235]
	v_mfma_f32_16x16x4_f32 v[232:235], v192, v11, v[232:235]
	v_mfma_f32_16x16x4_f32 v[232:235], v193, v94, v[232:235]
	v_mfma_f32_16x16x4_f32 v[232:235], v194, v95, v[232:235]
	v_mfma_f32_16x16x4_f32 v[232:235], v195, v24, v[232:235]
	v_mfma_f32_16x16x4_f32 v[232:235], v196, v103, v[232:235]
	v_mfma_f32_16x16x4_f32 v[232:235], v197, v28, v[232:235]
	v_mfma_f32_16x16x4_f32 v[232:235], v198, v29, v[232:235]
	v_mfma_f32_16x16x4_f32 v[232:235], v199, v36, v[232:235]
	v_mfma_f32_16x16x4_f32 v[232:235], v200, v37, v[232:235]
	v_mfma_f32_16x16x4_f32 v[232:235], v201, v40, v[232:235]
	v_mfma_f32_16x16x4_f32 v[232:235], v202, v41, v[232:235]
	v_mfma_f32_16x16x4_f32 v[232:235], v203, v44, v[232:235]
	v_mfma_f32_16x16x4_f32 v[232:235], v204, v54, v[232:235]
	v_mfma_f32_16x16x4_f32 v[232:235], v205, v55, v[232:235]
	v_mfma_f32_16x16x4_f32 v[232:235], v206, v62, v[232:235]
	v_mfma_f32_16x16x4_f32 v[232:235], v207, v63, v[232:235]
	v_mfma_f32_16x16x4_f32 v[232:235], v208, v68, v[232:235]
	v_mfma_f32_16x16x4_f32 v[232:235], v209, v69, v[232:235]
	v_mfma_f32_16x16x4_f32 v[232:235], v210, v72, v[232:235]
	v_mfma_f32_16x16x4_f32 v[232:235], v211, v73, v[232:235]
	v_mfma_f32_16x16x4_f32 v[232:235], v212, v116, v[232:235]
	v_mfma_f32_16x16x4_f32 v[232:235], v213, v118, v[232:235]
	s_nop 7
	s_nop 3
	ds_write_b32 v246, v220 offset:8192
	ds_write_b32 v246, v221 offset:10240
	ds_write_b32 v246, v222 offset:12288
	ds_write_b32 v246, v223 offset:14336
	ds_write_b32 v246, v224 offset:8256
	ds_write_b32 v246, v225 offset:10304
	ds_write_b32 v246, v226 offset:12352
	ds_write_b32 v246, v227 offset:14400
	ds_write_b32 v246, v228 offset:8320
	ds_write_b32 v246, v229 offset:10368
	ds_write_b32 v246, v230 offset:12416
	ds_write_b32 v246, v231 offset:14464
	ds_write_b32 v246, v232 offset:8384
	ds_write_b32 v246, v233 offset:10432
	ds_write_b32 v246, v234 offset:12480
	ds_write_b32 v246, v235 offset:14528
	s_waitcnt lgkmcnt(0)
.LBB0_94:
	s_or_b32 s46, s60, s56
	s_ashr_i32 s47, s46, 31
	s_lshl_b64 s[0:1], s[46:47], 9
	s_or_b32 s2, s60, s59
	v_lshl_add_u64 v[0:1], s[0:1], 0, v[4:5]
	s_mul_i32 s20, s46, 0x3600
	v_lshlrev_b64 v[0:1], 1, v[0:1]
	s_mul_hi_i32 s3, s46, 0x3600
	s_add_u32 s22, s94, s20
	v_lshl_add_u64 v[2:3], s[34:35], 0, v[0:1]
	v_lshl_add_u64 v[0:1], s[62:63], 0, v[0:1]
	s_addc_u32 s23, s95, s3
	v_lshlrev_b64 v[22:23], 1, v[4:5]
	v_sub_co_u32_e64 v139, s[52:53], s2, 1
	global_load_ushort v201, v[2:3], off
	global_load_ushort v202, v[0:1], off
	v_lshl_add_u64 v[0:1], s[22:23], 0, v[22:23]
	s_and_b64 s[24:25], s[52:53], exec
	v_add_co_u32_e32 v18, vcc, s75, v0
	s_cselect_b32 s25, 0, -1
	s_cselect_b32 s24, 0, 0xffffca00
	s_cmp_lt_u32 s2, s57
	v_lshl_add_u64 v[2:3], v[0:1], 0, s[68:69]
	v_addc_co_u32_e32 v19, vcc, 0, v1, vcc
	s_cselect_b64 s[44:45], -1, 0
	global_load_ushort v199, v[18:19], off offset:64
	v_lshl_add_u64 v[18:19], v[2:3], 0, s[24:25]
	s_and_b64 s[24:25], s[44:45], exec
	s_cselect_b32 s28, 0x3600, 0
	v_lshl_add_u64 v[2:3], v[2:3], 0, s[28:29]
	s_lshl_b64 s[24:25], s[46:47], 5
	global_load_ushort v208, v[18:19], off
	global_load_ushort v210, v[2:3], off
	s_add_u32 s24, s10, s24
	v_mov_b32_e32 v19, s1
	v_or_b32_e32 v18, s0, v10
	s_addc_u32 s25, s11, s25
	v_lshlrev_b64 v[18:19], 1, v[18:19]
	s_or_b32 s50, s46, 1
	v_lshl_add_u64 v[20:21], v[6:7], 0, v[18:19]
	v_lshl_add_u64 v[18:19], v[8:9], 0, v[18:19]
	s_ashr_i32 s51, s50, 31
	global_load_ushort v195, v[20:21], off
	global_load_ushort v193, v[18:19], off
	global_load_ushort v196, v[20:21], off offset:128
	global_load_ushort v194, v[18:19], off offset:128
	global_load_ushort v192, v134, s[22:23]
	global_load_ushort v191, v134, s[22:23] offset:128
	v_add_co_u32_e32 v18, vcc, s96, v0
	s_or_b32 s3, s2, 1
	s_lshl_b64 s[0:1], s[50:51], 9
	s_mul_i32 s22, s50, 0x3600
	v_addc_co_u32_e32 v19, vcc, 0, v1, vcc
	s_mul_hi_i32 s20, s50, 0x3600
	s_add_u32 s22, s94, s22
	global_load_ushort v138, v[18:19], off offset:3136
	v_lshl_add_u64 v[18:19], s[0:1], 0, v[4:5]
	s_addc_u32 s23, s95, s20
	v_lshlrev_b64 v[18:19], 1, v[18:19]
	s_cmp_lt_u32 s3, s57
	v_lshl_add_u64 v[20:21], s[34:35], 0, v[18:19]
	v_lshl_add_u64 v[18:19], s[62:63], 0, v[18:19]
	s_cselect_b64 s[42:43], -1, 0
	v_lshl_add_u64 v[2:3], s[24:25], 0, v[16:17]
	global_load_ushort v212, v[20:21], off
	global_load_ushort v213, v[18:19], off
	v_lshl_add_u64 v[20:21], s[22:23], 0, v[22:23]
	s_and_b64 s[24:25], s[42:43], exec
	v_lshl_add_u64 v[18:19], v[20:21], 0, s[68:69]
	v_add_co_u32_e32 v136, vcc, s75, v20
	s_cselect_b32 s28, 0x3600, 0
	s_nop 0
	v_addc_co_u32_e32 v137, vcc, 0, v21, vcc
	v_lshl_add_u64 v[18:19], v[18:19], 0, s[28:29]
	s_lshl_b64 s[24:25], s[50:51], 5
	global_load_ushort v198, v[136:137], off offset:64
	global_load_ushort v206, v[18:19], off
	s_add_u32 s24, s10, s24
	v_mov_b32_e32 v137, s1
	v_or_b32_e32 v136, s0, v10
	s_addc_u32 s25, s11, s25
	v_lshlrev_b64 v[136:137], 1, v[136:137]
	s_or_b32 s48, s46, 2
	v_lshl_add_u64 v[140:141], v[6:7], 0, v[136:137]
	v_lshl_add_u64 v[136:137], v[8:9], 0, v[136:137]
	s_ashr_i32 s49, s48, 31
	global_load_ushort v167, v[140:141], off
	global_load_ushort v165, v[136:137], off
	global_load_ushort v190, v[140:141], off offset:128
	global_load_ushort v166, v[136:137], off offset:128
	global_load_ushort v164, v134, s[22:23]
	global_load_ushort v163, v134, s[22:23] offset:128
	v_add_co_u32_e32 v20, vcc, s96, v20
	s_or_b32 s23, s2, 2
	s_lshl_b64 s[0:1], s[48:49], 9
	s_mul_i32 s22, s48, 0x3600
	v_lshl_add_u64 v[18:19], s[24:25], 0, v[16:17]
; __device__ void phase_combine(const P& p, int l, int ntok, float* lds) {
;     ...
;       for (int i = 0; i < 4; ++i) {
;         int row = r0 + i0 + i, t = tb + i0 + i;
;         y0[i] = or0[(size_t)row * 512 + tid]; y1[i] = or1[(size_t)row * 512 + tid];
;         const u16* pv = p.projb + (size_t)row * PROJP + O_RKV + 1024 + tid;
;         vc[i] = pv[0]; vp[i] = pv[t > 0 ? -PROJP : 0]; vn[i] = pv[t < T - 1 ? PROJP : 0];
;         sf[i] = p.sbon[(size_t)row * 8 + wv]; sb[i] = p.sbon[(size_t)NT * 8 + (size_t)row * 8 + wv];
;         size_t ob = (size_t)row * 512 + hh * 128 + lane;
;         a0[i] = om0[ob]; a1[i] = om1[ob]; a2[i] = om0[ob + 64]; a3[i] = om1[ob + 64];
;         const u16* pg = p.projb + (size_t)row * PROJP + gch;
;         g0r[i] = pg[0]; g1r[i] = pg[64];
;         cbr[i] = p.projb[(size_t)row * PROJP + O_CB + tid];
;       }
;     ...
;             float4 s = *reinterpret_cast<const float4*>(sig + (i0 + i) * 96 + m);
;             gate[i] += s.x * g2r[m] + s.y * g2r[m + 1] + s.z * g2r[m + 2] + s.w * g2r[m + 3];
;           }
;         }
	v_addc_co_u32_e32 v21, vcc, 0, v21, vcc
	s_mul_hi_i32 s20, s48, 0x3600
	s_add_u32 s24, s94, s22
	global_load_ushort v137, v[20:21], off offset:3136
	v_lshl_add_u64 v[20:21], s[0:1], 0, v[4:5]
	s_addc_u32 s25, s95, s20
	v_lshlrev_b64 v[20:21], 1, v[20:21]
	s_cmp_lt_u32 s23, s57
	v_lshl_add_u64 v[140:141], s[34:35], 0, v[20:21]
	v_lshl_add_u64 v[20:21], s[62:63], 0, v[20:21]
	s_cselect_b64 s[40:41], -1, 0
	global_load_ushort v209, v[140:141], off
	global_load_ushort v211, v[20:21], off
	v_lshl_add_u64 v[140:141], s[24:25], 0, v[22:23]
	s_and_b64 s[26:27], s[40:41], exec
	v_lshl_add_u64 v[20:21], v[140:141], 0, s[68:69]
	v_add_co_u32_e32 v142, vcc, s75, v140
	s_cselect_b32 s28, 0x3600, 0
	s_lshl_b64 s[26:27], s[48:49], 5
	v_addc_co_u32_e32 v143, vcc, 0, v141, vcc
	v_lshl_add_u64 v[20:21], v[20:21], 0, s[28:29]
	s_add_u32 s26, s10, s26
	global_load_ushort v197, v[142:143], off offset:64
	global_load_ushort v204, v[20:21], off
	s_addc_u32 s27, s11, s27
	v_mov_b32_e32 v143, s1
	v_or_b32_e32 v142, s0, v10
	s_or_b32 s36, s46, 3
	v_lshlrev_b64 v[142:143], 1, v[142:143]
	v_add_co_u32_e32 v140, vcc, s96, v140
	s_ashr_i32 s37, s36, 31
	v_lshl_add_u64 v[144:145], v[6:7], 0, v[142:143]
	v_lshl_add_u64 v[142:143], v[8:9], 0, v[142:143]
	v_addc_co_u32_e32 v141, vcc, 0, v141, vcc
	s_lshl_b64 s[0:1], s[36:37], 9
	v_lshl_add_u64 v[20:21], s[26:27], 0, v[16:17]
	global_load_ushort v161, v[144:145], off
	global_load_ushort v159, v[142:143], off
	global_load_ushort v162, v[144:145], off offset:128
	global_load_ushort v160, v[142:143], off offset:128
	global_load_ushort v158, v134, s[24:25]
	global_load_ushort v157, v134, s[24:25] offset:128
	global_load_ushort v136, v[140:141], off offset:3136
	s_or_b32 s26, s2, 3
	v_lshl_add_u64 v[140:141], s[0:1], 0, v[4:5]
	s_mul_i32 s22, s36, 0x3600
	v_lshlrev_b64 v[140:141], 1, v[140:141]
	s_mul_hi_i32 s20, s36, 0x3600
	s_add_u32 s24, s94, s22
	v_lshl_add_u64 v[142:143], s[34:35], 0, v[140:141]
	v_lshl_add_u64 v[140:141], s[62:63], 0, v[140:141]
	s_addc_u32 s25, s95, s20
	global_load_ushort v205, v[142:143], off
	global_load_ushort v207, v[140:141], off
	v_lshl_add_u64 v[140:141], s[24:25], 0, v[22:23]
	v_add_co_u32_e32 v142, vcc, s75, v140
	s_cmp_lt_u32 s26, s57
	s_nop 0
	v_addc_co_u32_e32 v143, vcc, 0, v141, vcc
	s_cselect_b64 vcc, -1, 0
	s_and_b64 s[30:31], vcc, exec
	v_lshl_add_u64 v[22:23], v[140:141], 0, s[68:69]
	s_cselect_b32 s28, 0x3600, 0
	v_lshl_add_u64 v[22:23], v[22:23], 0, s[28:29]
	global_load_ushort v200, v[142:143], off offset:64
	global_load_ushort v203, v[22:23], off
	v_mov_b32_e32 v143, s1
	v_or_b32_e32 v142, s0, v10
	v_min_i32_e32 v139, s57, v139
	v_lshlrev_b64 v[142:143], 1, v[142:143]
	v_add_co_u32_e64 v140, s[0:1], s96, v140
	v_cndmask_b32_e64 v139, v139, 0, s[52:53]
	v_lshl_add_u64 v[144:145], v[6:7], 0, v[142:143]
	v_lshl_add_u64 v[142:143], v[8:9], 0, v[142:143]
	v_addc_co_u32_e64 v141, s[0:1], 0, v141, s[0:1]
	v_subrev_u32_e32 v139, s2, v139
	global_load_ushort v155, v[144:145], off
	global_load_ushort v153, v[142:143], off
	global_load_ushort v156, v[144:145], off offset:128
	global_load_ushort v154, v[142:143], off offset:128
	global_load_ushort v152, v134, s[24:25]
	global_load_ushort v149, v134, s[24:25] offset:128
	global_load_ushort v135, v[140:141], off offset:3136
	v_mad_i64_i32 v[140:141], s[0:1], v139, s61, v[0:1]
	v_add_co_u32_e64 v140, s[0:1], s78, v140
	s_lshl_b64 s[30:31], s[36:37], 5
	s_nop 0
	v_addc_co_u32_e64 v141, s[0:1], 0, v141, s[0:1]
	global_load_ushort v139, v[140:141], off offset:64
	s_nop 0
	global_load_ushort v140, v[140:141], off offset:1088
	v_mov_b32_e32 v141, s57
	v_sub_u32_e64 v141, s2, v141 clamp
	v_sub_u32_e32 v141, 0, v141
	v_mad_i64_i32 v[142:143], s[0:1], v141, s61, v[0:1]
	v_add_co_u32_e64 v142, s[0:1], s78, v142
	s_add_u32 s30, s10, s30
	s_nop 0
	v_addc_co_u32_e64 v143, s[0:1], 0, v143, s[0:1]
	s_addc_u32 s31, s11, s31
	s_min_u32 s0, s3, s57
	s_sub_i32 s0, s0, s2
	global_load_ushort v147, v[142:143], off offset:64
	global_load_ushort v148, v[142:143], off offset:1088
	v_mad_i64_i32 v[142:143], s[0:1], s0, v179, v[0:1]
	v_add_co_u32_e64 v142, s[0:1], s78, v142
	v_lshl_add_u64 v[22:23], s[30:31], 0, v[16:17]
	s_nop 0
	v_addc_co_u32_e64 v143, s[0:1], 0, v143, s[0:1]
	s_min_u32 s0, s23, s57
	s_sub_i32 s0, s0, s2
	global_load_ushort v150, v[142:143], off offset:64
	global_load_ushort v151, v[142:143], off offset:1088
	v_mad_i64_i32 v[142:143], s[0:1], s0, v179, v[0:1]
	v_add_co_u32_e64 v142, s[0:1], s78, v142
	s_waitcnt vmcnt(25)
	v_mov_b32_e32 v216, v197
	v_addc_co_u32_e64 v143, s[0:1], 0, v143, s[0:1]
	s_min_u32 s0, s26, s57
	s_sub_i32 s0, s0, s2
	global_load_ushort v145, v[142:143], off offset:64
	global_load_ushort v146, v[142:143], off offset:1088
	v_mad_i64_i32 v[142:143], s[0:1], s0, v179, v[0:1]
	v_add_co_u32_e64 v214, s[0:1], s78, v142
	s_nop 1
	v_addc_co_u32_e64 v215, s[0:1], 0, v143, s[0:1]
	s_add_i32 s0, s2, 4
	s_min_u32 s0, s0, s57
	s_sub_i32 s0, s0, s2
	v_mad_i64_i32 v[0:1], s[0:1], s0, v179, v[0:1]
	v_add_co_u32_e64 v0, s[0:1], s78, v0
	global_load_ushort v143, v[214:215], off offset:64
	global_load_ushort v144, v[214:215], off offset:1088
	v_addc_co_u32_e64 v1, s[0:1], 0, v1, s[0:1]
	global_load_ushort v141, v[0:1], off offset:64
	global_load_ushort v142, v[0:1], off offset:1088
	global_load_dword v218, v[2:3], off
	global_load_dword v214, v[22:23], off
	global_load_dword v215, v[20:21], off
	global_load_dword v217, v[18:19], off
	v_add_co_u32_e64 v0, s[0:1], s66, v2
	s_lshl_b64 s[2:3], s[48:49], 12
	s_nop 0
	v_addc_co_u32_e64 v1, s[0:1], 0, v3, s[0:1]
	global_load_dword v219, v[0:1], off
	v_add_co_u32_e64 v0, s[0:1], s66, v22
	s_nop 1
	v_addc_co_u32_e64 v1, s[0:1], 0, v23, s[0:1]
	global_load_dword v22, v[0:1], off
	v_add_co_u32_e64 v0, s[0:1], s66, v20
	s_nop 1
	v_addc_co_u32_e64 v1, s[0:1], 0, v21, s[0:1]
	global_load_dword v23, v[0:1], off
	v_add_co_u32_e64 v0, s[0:1], s66, v18
	v_mov_b32_e32 v21, v198
	s_nop 0
	v_addc_co_u32_e64 v1, s[0:1], 0, v19, s[0:1]
	s_mul_i32 s0, s60, 0x180
	s_add_i32 s0, s0, 0
	global_load_dword v20, v[0:1], off
	v_mov_b32_e32 v18, v199
	v_mov_b32_e32 v19, s0
	v_lshlrev_b32_e32 v244, 2, v168
	v_lshl_add_u32 v244, s60, 11, v244
	ds_read_b32 v221, v244 offset:8192
	ds_read_b32 v222, v244 offset:10240
	ds_read_b32 v223, v244 offset:12288
	ds_read_b32 v0, v244 offset:14336
	s_waitcnt vmcnt(30)
; __device__ __forceinline__ float bf2f(u16 v) { return __uint_as_float(((unsigned)v) << 16); }
; __device__ void phase_combine(const P& p, int l, int ntok, float* lds) {
;     ...
;         for (int i = 0; i < 4; ++i) {
;           int row = r0 + i0 + i, t = tb + i0 + i;
;           float yv = bf2f((u16)y0[i]) + bf2f((u16)y1[i]);
;           float mean = wave_sum_b(yv) * (1.f / 64.f);
;           float d = yv - mean;
;           float var = wave_sum_b(d * d) * (1.f / 64.f);
;           float yn = d * rsqrtf(var + 64e-5f) * gnw + gnb;
;           float v_c = bf2f((u16)vc[i]), v_p = t > 0 ? bf2f((u16)vp[i]) : 0.f, v_n = t < T - 1 ? bf2f((u16)vn[i]) : 0.f;
;           float vf = v_c + (v_p - v_c) * muvf, vb = v_c + (v_n - v_c) * muvb;
;           float bonus = sf[i] * vf + sb[i] * vb;
;           p.nbuf[(size_t)row * D + 1536 + tid] = f2bf((yn + bonus) * gate[i]);
;         }
	s_waitcnt vmcnt(29)
	s_waitcnt vmcnt(4)
	s_waitcnt vmcnt(0)
	s_waitcnt lgkmcnt(0)
	v_lshlrev_b32_e32 v197, 16, v197
	v_lshlrev_b32_e32 v192, 16, v192
	v_lshlrev_b32_e32 v164, 16, v164
	v_lshlrev_b32_e32 v158, 16, v158
	v_lshlrev_b32_e32 v152, 16, v152
	v_lshlrev_b32_e32 v138, 16, v138
	v_lshlrev_b32_e32 v1, 16, v201
	v_lshlrev_b32_e32 v2, 16, v202
	v_add_f32_e32 v1, v2, v1
	v_mov_b32_e32 v3, v129
	s_nop 0
	v_add_f32_dpp v2, v1, v1 quad_perm:[1,0,3,2] row_mask:0xf bank_mask:0xf bound_ctrl:1
	s_nop 1
	v_add_f32_dpp v2, v2, v2 quad_perm:[2,3,0,1] row_mask:0xf bank_mask:0xf bound_ctrl:1
	s_nop 1
	v_add_f32_dpp v2, v2, v2 row_half_mirror row_mask:0xf bank_mask:0xf bound_ctrl:1
	s_nop 1
	v_add_f32_dpp v2, v2, v2 row_mirror row_mask:0xf bank_mask:0xf bound_ctrl:1
	s_nop 1
	v_mov_b32_dpp v3, v2 row_bcast:15 row_mask:0xa bank_mask:0xf
	v_add_f32_e32 v2, v2, v3
	v_mov_b32_e32 v3, v129
	s_nop 1
	v_mov_b32_dpp v3, v2 row_bcast:31 row_mask:0xc bank_mask:0xf
	v_add_f32_e32 v2, v2, v3
	v_mov_b32_e32 v3, v129
	v_readlane_b32 s0, v2, 63
	s_nop 1
	v_fmac_f32_e32 v1, s0, v180
	v_mul_f32_e32 v2, v1, v1
	s_nop 1
	v_mov_b32_dpp v2, v2 quad_perm:[1,0,3,2] row_mask:0xf bank_mask:0xf bound_ctrl:1
	v_fmac_f32_e32 v2, v1, v1
	s_nop 1
	v_add_f32_dpp v2, v2, v2 quad_perm:[2,3,0,1] row_mask:0xf bank_mask:0xf bound_ctrl:1
	s_nop 1
	v_add_f32_dpp v2, v2, v2 row_half_mirror row_mask:0xf bank_mask:0xf bound_ctrl:1
	s_nop 1
	v_add_f32_dpp v2, v2, v2 row_mirror row_mask:0xf bank_mask:0xf bound_ctrl:1
	s_nop 1
	v_mov_b32_dpp v3, v2 row_bcast:15 row_mask:0xa bank_mask:0xf
	v_add_f32_e32 v2, v2, v3
	v_mov_b32_e32 v3, v129
	s_nop 1
	v_mov_b32_dpp v3, v2 row_bcast:31 row_mask:0xc bank_mask:0xf
	v_add_f32_e32 v2, v2, v3
	s_nop 0
	v_readlane_b32 s0, v2, 63
	s_nop 1
	v_fma_f32 v2, s0, v181, v170
	v_cmp_gt_f32_e64 s[0:1], s33, v2
	v_mul_f32_e32 v3, 0x4b800000, v2
	s_nop 0
	v_cndmask_b32_e64 v2, v2, v3, s[0:1]
	v_rsq_f32_e32 v2, v2
	s_nop 0
	v_mul_f32_e32 v3, 0x45800000, v2
	v_cndmask_b32_e64 v2, v2, v3, s[0:1]
	v_mul_f32_e32 v1, v1, v2
	v_lshlrev_b32_e32 v2, 16, v18
	v_lshlrev_b32_e32 v3, 16, v208
	v_lshlrev_b32_e32 v18, 16, v210
	v_cndmask_b32_e64 v3, v3, 0, s[52:53]
	v_cndmask_b32_e64 v18, 0, v18, s[44:45]
	v_sub_f32_e32 v3, v3, v2
	v_sub_f32_e32 v18, v18, v2
	v_fma_f32 v3, v121, v3, v2
	v_fmac_f32_e32 v2, v122, v18
	v_mul_f32_e32 v2, v219, v2
	v_fma_f32 v1, v119, v1, v120
	v_fmac_f32_e32 v2, v218, v3
	v_add_f32_e32 v1, v2, v1
	v_mul_f32_e32 v1, v221, v1
	v_bfe_u32 v2, v1, 16, 1
	s_lshl_b64 s[44:45], s[46:47], 12
	v_add3_u32 v1, v1, v2, s21
	v_lshl_add_u64 v[18:19], v[14:15], 0, s[44:45]
	global_store_short_d16_hi v[18:19], v1, off offset:3072
	v_lshlrev_b32_e32 v1, 16, v212
	v_lshlrev_b32_e32 v2, 16, v213
	v_add_f32_e32 v1, v2, v1
	v_mov_b32_e32 v3, v129
	s_nop 0
	v_add_f32_dpp v2, v1, v1 quad_perm:[1,0,3,2] row_mask:0xf bank_mask:0xf bound_ctrl:1
	s_nop 1
	v_add_f32_dpp v2, v2, v2 quad_perm:[2,3,0,1] row_mask:0xf bank_mask:0xf bound_ctrl:1
	s_nop 1
	v_add_f32_dpp v2, v2, v2 row_half_mirror row_mask:0xf bank_mask:0xf bound_ctrl:1
	s_nop 1
	v_add_f32_dpp v2, v2, v2 row_mirror row_mask:0xf bank_mask:0xf bound_ctrl:1
	s_nop 1
	v_mov_b32_dpp v3, v2 row_bcast:15 row_mask:0xa bank_mask:0xf
	v_add_f32_e32 v2, v2, v3
	v_mov_b32_e32 v3, v129
	s_nop 1
	v_mov_b32_dpp v3, v2 row_bcast:31 row_mask:0xc bank_mask:0xf
	v_add_f32_e32 v2, v2, v3
	v_mov_b32_e32 v3, v129
	v_readlane_b32 s0, v2, 63
	s_nop 1
	v_fmac_f32_e32 v1, s0, v180
	v_mul_f32_e32 v2, v1, v1
	s_nop 1
	v_mov_b32_dpp v2, v2 quad_perm:[1,0,3,2] row_mask:0xf bank_mask:0xf bound_ctrl:1
	v_fmac_f32_e32 v2, v1, v1
	s_nop 1
	v_add_f32_dpp v2, v2, v2 quad_perm:[2,3,0,1] row_mask:0xf bank_mask:0xf bound_ctrl:1
	s_nop 1
	v_add_f32_dpp v2, v2, v2 row_half_mirror row_mask:0xf bank_mask:0xf bound_ctrl:1
	s_nop 1
	v_add_f32_dpp v2, v2, v2 row_mirror row_mask:0xf bank_mask:0xf bound_ctrl:1
	s_nop 1
	v_mov_b32_dpp v3, v2 row_bcast:15 row_mask:0xa bank_mask:0xf
	v_add_f32_e32 v2, v2, v3
	v_mov_b32_e32 v3, v129
	s_nop 1
	v_mov_b32_dpp v3, v2 row_bcast:31 row_mask:0xc bank_mask:0xf
	v_add_f32_e32 v2, v2, v3
	s_nop 0
	v_readlane_b32 s0, v2, 63
	s_nop 1
	v_fma_f32 v2, s0, v181, v170
	v_cmp_gt_f32_e64 s[0:1], s33, v2
	v_mul_f32_e32 v3, 0x4b800000, v2
	s_nop 0
	v_cndmask_b32_e64 v2, v2, v3, s[0:1]
	v_rsq_f32_e32 v2, v2
	s_nop 0
	v_mul_f32_e32 v3, 0x45800000, v2
	v_cndmask_b32_e64 v2, v2, v3, s[0:1]
	v_mul_f32_e32 v1, v1, v2
	v_lshlrev_b32_e32 v2, 16, v21
	v_lshlrev_b32_e32 v21, 16, v206
	v_lshlrev_b32_e32 v3, 16, v199
	v_cndmask_b32_e64 v21, 0, v21, s[42:43]
	v_sub_f32_e32 v3, v3, v2
	v_sub_f32_e32 v21, v21, v2
	v_fma_f32 v3, v121, v3, v2
	v_fmac_f32_e32 v2, v122, v21
	v_mul_f32_e32 v2, v20, v2
	v_fma_f32 v1, v119, v1, v120
	v_fmac_f32_e32 v2, v217, v3
	v_add_f32_e32 v1, v2, v1
	v_mul_f32_e32 v1, v222, v1
	v_bfe_u32 v2, v1, 16, 1
	s_lshl_b64 s[42:43], s[50:51], 12
	v_add3_u32 v1, v1, v2, s21
	v_lshl_add_u64 v[20:21], v[14:15], 0, s[42:43]
	global_store_short_d16_hi v[20:21], v1, off offset:3072
	v_lshlrev_b32_e32 v1, 16, v209
	v_lshlrev_b32_e32 v2, 16, v211
	v_add_f32_e32 v1, v2, v1
	v_mov_b32_e32 v3, v129
	s_nop 0
	v_add_f32_dpp v2, v1, v1 quad_perm:[1,0,3,2] row_mask:0xf bank_mask:0xf bound_ctrl:1
	s_nop 1
	v_add_f32_dpp v2, v2, v2 quad_perm:[2,3,0,1] row_mask:0xf bank_mask:0xf bound_ctrl:1
	s_nop 1
	v_add_f32_dpp v2, v2, v2 row_half_mirror row_mask:0xf bank_mask:0xf bound_ctrl:1
	s_nop 1
	v_add_f32_dpp v2, v2, v2 row_mirror row_mask:0xf bank_mask:0xf bound_ctrl:1
	s_nop 1
	v_mov_b32_dpp v3, v2 row_bcast:15 row_mask:0xa bank_mask:0xf
	v_add_f32_e32 v2, v2, v3
	v_mov_b32_e32 v3, v129
	s_nop 1
	v_mov_b32_dpp v3, v2 row_bcast:31 row_mask:0xc bank_mask:0xf
; __device__ __forceinline__ float bf2f(u16 v) { return __uint_as_float(((unsigned)v) << 16); }
; __device__ __forceinline__ float siluf_(float x) { return x / (1.f + __expf(-x)); }
; __device__ void phase_combine(const P& p, int l, int ntok, float* lds) {
;     ...
;         for (int i = 0; i < 4; ++i) {
;           int row = r0 + i0 + i, t = tb + i0 + i;
;           float yv = bf2f((u16)y0[i]) + bf2f((u16)y1[i]);
;           float mean = wave_sum_b(yv) * (1.f / 64.f);
;           float d = yv - mean;
;           float var = wave_sum_b(d * d) * (1.f / 64.f);
;           float yn = d * rsqrtf(var + 64e-5f) * gnw + gnb;
;           float v_c = bf2f((u16)vc[i]), v_p = t > 0 ? bf2f((u16)vp[i]) : 0.f, v_n = t < T - 1 ? bf2f((u16)vn[i]) : 0.f;
;           float vf = v_c + (v_p - v_c) * muvf, vb = v_c + (v_n - v_c) * muvb;
;           float bonus = sf[i] * vf + sb[i] * vb;
;           p.nbuf[(size_t)row * D + 1536 + tid] = f2bf((yn + bonus) * gate[i]);
;         }
;       }
; #pragma unroll
;       for (int i = 0; i < 4; ++i) {
;         int row = r0 + i0 + i;
;         float o0 = bf2f((u16)a0[i]) + bf2f((u16)a1[i]), o1 = bf2f((u16)a2[i]) + bf2f((u16)a3[i]);
;         float ss = wave_sum_b(o0 * o0 + o1 * o1);
;         float rstd = rsqrtf(ss * (1.f / 128.f) + 1e-6f);
;         u16* dst = p.nbuf + (size_t)row * D + mixer * 512 + hh * 128 + lane;
;         dst[0] = f2bf(o0 * rstd * ng0 * siluf_(bf2f((u16)g0r[i])));
;         dst[64] = f2bf(o1 * rstd * ng1 * siluf_(bf2f((u16)g1r[i])));
	v_add_f32_e32 v2, v2, v3
	v_mov_b32_e32 v3, v129
	v_readlane_b32 s0, v2, 63
	s_nop 1
	v_fmac_f32_e32 v1, s0, v180
	v_mul_f32_e32 v2, v1, v1
	s_nop 1
	v_mov_b32_dpp v2, v2 quad_perm:[1,0,3,2] row_mask:0xf bank_mask:0xf bound_ctrl:1
	v_fmac_f32_e32 v2, v1, v1
	s_nop 1
	v_add_f32_dpp v2, v2, v2 quad_perm:[2,3,0,1] row_mask:0xf bank_mask:0xf bound_ctrl:1
	s_nop 1
	v_add_f32_dpp v2, v2, v2 row_half_mirror row_mask:0xf bank_mask:0xf bound_ctrl:1
	s_nop 1
	v_add_f32_dpp v2, v2, v2 row_mirror row_mask:0xf bank_mask:0xf bound_ctrl:1
	s_nop 1
	v_mov_b32_dpp v3, v2 row_bcast:15 row_mask:0xa bank_mask:0xf
	v_add_f32_e32 v2, v2, v3
	v_mov_b32_e32 v3, v129
	s_nop 1
	v_mov_b32_dpp v3, v2 row_bcast:31 row_mask:0xc bank_mask:0xf
	v_add_f32_e32 v2, v2, v3
	s_nop 0
	v_readlane_b32 s0, v2, 63
	s_nop 1
	v_fma_f32 v2, s0, v181, v170
	v_cmp_gt_f32_e64 s[0:1], s33, v2
	v_mul_f32_e32 v3, 0x4b800000, v2
	s_nop 0
	v_cndmask_b32_e64 v2, v2, v3, s[0:1]
	v_rsq_f32_e32 v2, v2
	s_nop 0
	v_mul_f32_e32 v3, 0x45800000, v2
	v_cndmask_b32_e64 v2, v2, v3, s[0:1]
	v_lshlrev_b32_e32 v3, 16, v198
	v_lshlrev_b32_e32 v198, 16, v204
	v_mul_f32_e32 v1, v1, v2
	v_lshlrev_b32_e32 v2, 16, v216
	v_cndmask_b32_e64 v198, 0, v198, s[40:41]
	v_sub_f32_e32 v3, v3, v2
	v_sub_f32_e32 v198, v198, v2
	v_fma_f32 v3, v121, v3, v2
	v_fmac_f32_e32 v2, v122, v198
	v_mul_f32_e32 v2, v23, v2
	v_fma_f32 v1, v119, v1, v120
	v_fmac_f32_e32 v2, v215, v3
	v_add_f32_e32 v1, v2, v1
	v_mul_f32_e32 v1, v223, v1
	v_bfe_u32 v2, v1, 16, 1
	v_add3_u32 v1, v1, v2, s21
	v_lshl_add_u64 v[2:3], v[14:15], 0, s[2:3]
	global_store_short_d16_hi v[2:3], v1, off offset:3072
	v_lshlrev_b32_e32 v1, 16, v205
	v_lshlrev_b32_e32 v23, 16, v207
	v_add_f32_e32 v1, v23, v1
	v_mov_b32_e32 v198, v129
	s_nop 0
	v_add_f32_dpp v23, v1, v1 quad_perm:[1,0,3,2] row_mask:0xf bank_mask:0xf bound_ctrl:1
	s_nop 1
	v_add_f32_dpp v23, v23, v23 quad_perm:[2,3,0,1] row_mask:0xf bank_mask:0xf bound_ctrl:1
	s_nop 1
	v_add_f32_dpp v23, v23, v23 row_half_mirror row_mask:0xf bank_mask:0xf bound_ctrl:1
	s_nop 1
	v_add_f32_dpp v23, v23, v23 row_mirror row_mask:0xf bank_mask:0xf bound_ctrl:1
	s_nop 1
	v_mov_b32_dpp v198, v23 row_bcast:15 row_mask:0xa bank_mask:0xf
	v_add_f32_e32 v23, v23, v198
	v_mov_b32_e32 v198, v129
	s_nop 1
	v_mov_b32_dpp v198, v23 row_bcast:31 row_mask:0xc bank_mask:0xf
	v_add_f32_e32 v23, v23, v198
	v_mov_b32_e32 v198, v129
	v_readlane_b32 s0, v23, 63
	s_nop 1
	v_fmac_f32_e32 v1, s0, v180
	v_mul_f32_e32 v23, v1, v1
	s_nop 1
	v_mov_b32_dpp v23, v23 quad_perm:[1,0,3,2] row_mask:0xf bank_mask:0xf bound_ctrl:1
	v_fmac_f32_e32 v23, v1, v1
	s_nop 1
	v_add_f32_dpp v23, v23, v23 quad_perm:[2,3,0,1] row_mask:0xf bank_mask:0xf bound_ctrl:1
	s_nop 1
	v_add_f32_dpp v23, v23, v23 row_half_mirror row_mask:0xf bank_mask:0xf bound_ctrl:1
	s_nop 1
	v_add_f32_dpp v23, v23, v23 row_mirror row_mask:0xf bank_mask:0xf bound_ctrl:1
	s_nop 1
	v_mov_b32_dpp v198, v23 row_bcast:15 row_mask:0xa bank_mask:0xf
	v_add_f32_e32 v23, v23, v198
	v_mov_b32_e32 v198, v129
	s_nop 1
	v_mov_b32_dpp v198, v23 row_bcast:31 row_mask:0xc bank_mask:0xf
	v_add_f32_e32 v23, v23, v198
	s_nop 0
	v_readlane_b32 s0, v23, 63
	s_nop 1
	v_fma_f32 v23, s0, v181, v170
	v_cmp_gt_f32_e64 s[0:1], s33, v23
	v_mul_f32_e32 v198, 0x4b800000, v23
	s_nop 0
	v_cndmask_b32_e64 v23, v23, v198, s[0:1]
	v_rsq_f32_e32 v23, v23
	s_nop 0
	v_mul_f32_e32 v198, 0x45800000, v23
	v_cndmask_b32_e64 v23, v23, v198, s[0:1]
	v_lshlrev_b32_e32 v198, 16, v203
	v_mul_f32_e32 v1, v1, v23
	v_lshlrev_b32_e32 v23, 16, v200
	v_cndmask_b32_e32 v198, 0, v198, vcc
	v_sub_f32_e32 v197, v197, v23
	v_sub_f32_e32 v198, v198, v23
	v_fma_f32 v197, v121, v197, v23
	v_fmac_f32_e32 v23, v122, v198
	v_mul_f32_e32 v22, v22, v23
	v_fma_f32 v1, v119, v1, v120
	v_fmac_f32_e32 v22, v214, v197
	v_add_f32_e32 v1, v22, v1
	v_mul_f32_e32 v0, v0, v1
	v_bfe_u32 v1, v0, 16, 1
	s_lshl_b64 s[0:1], s[36:37], 12
	v_add3_u32 v22, v0, v1, s21
	v_lshl_add_u64 v[0:1], v[14:15], 0, s[0:1]
	global_store_short_d16_hi v[0:1], v22, off offset:3072
	v_lshlrev_b32_e32 v22, 16, v195
	v_lshlrev_b32_e32 v23, 16, v196
	v_lshlrev_b32_e32 v196, 16, v193
	v_lshlrev_b32_e32 v197, 16, v194
	v_pk_add_f32 v[22:23], v[22:23], v[196:197]
	v_mul_f32_e32 v196, 0xbfb8aa3b, v192
	v_pk_mul_f32 v[194:195], v[22:23], v[22:23]
	v_exp_f32_e32 v196, v196
	v_add_f32_e32 v193, v194, v195
	v_mov_b32_e32 v194, v129
	v_add_f32_e32 v196, 1.0, v196
	v_add_f32_dpp v193, v193, v193 quad_perm:[1,0,3,2] row_mask:0xf bank_mask:0xf bound_ctrl:1
	s_nop 0
	s_nop 0
	v_add_f32_dpp v193, v193, v193 quad_perm:[2,3,0,1] row_mask:0xf bank_mask:0xf bound_ctrl:1
	s_nop 0
	s_nop 0
	v_add_f32_dpp v193, v193, v193 row_half_mirror row_mask:0xf bank_mask:0xf bound_ctrl:1
	s_nop 0
	s_nop 0
	v_add_f32_dpp v193, v193, v193 row_mirror row_mask:0xf bank_mask:0xf bound_ctrl:1
	s_nop 0
	s_nop 0
	v_mov_b32_dpp v194, v193 row_bcast:15 row_mask:0xa bank_mask:0xf
	v_add_f32_e32 v193, v193, v194
	v_mov_b32_e32 v194, v129
	s_nop 1
	v_mov_b32_dpp v194, v193 row_bcast:31 row_mask:0xc bank_mask:0xf
	v_add_f32_e32 v193, v193, v194
	s_nop 0
	v_readlane_b32 s20, v193, 63
	s_nop 1
	v_fma_f32 v193, s20, v182, v169
	v_cmp_gt_f32_e32 vcc, s33, v193
	v_mul_f32_e32 v194, 0x4b800000, v193
	s_nop 0
	v_cndmask_b32_e32 v193, v193, v194, vcc
	v_rsq_f32_e32 v193, v193
	s_nop 0
	v_mul_f32_e32 v194, 0x45800000, v193
	v_cndmask_b32_e32 v193, v193, v194, vcc
	v_mul_f32_e32 v22, v22, v193
	v_mul_f32_e32 v22, v126, v22
	v_rcp_f32_e32 v197, v196
	s_nop 0
	v_mul_f32_e32 v192, v192, v197
	v_mul_f32_e32 v22, v192, v22
	v_bfe_u32 v192, v22, 16, 1
	v_lshl_add_u64 v[194:195], v[12:13], 0, s[44:45]
	v_add3_u32 v22, v22, v192, s21
; __device__ __forceinline__ float bf2f(u16 v) { return __uint_as_float(((unsigned)v) << 16); }
; __device__ __forceinline__ float siluf_(float x) { return x / (1.f + __expf(-x)); }
; __device__ void phase_combine(const P& p, int l, int ntok, float* lds) {
;     ...
;       for (int i = 0; i < 4; ++i) {
;         int row = r0 + i0 + i;
;         float o0 = bf2f((u16)a0[i]) + bf2f((u16)a1[i]), o1 = bf2f((u16)a2[i]) + bf2f((u16)a3[i]);
;         float ss = wave_sum_b(o0 * o0 + o1 * o1);
;         float rstd = rsqrtf(ss * (1.f / 128.f) + 1e-6f);
;         u16* dst = p.nbuf + (size_t)row * D + mixer * 512 + hh * 128 + lane;
;         dst[0] = f2bf(o0 * rstd * ng0 * siluf_(bf2f((u16)g0r[i])));
;         dst[64] = f2bf(o1 * rstd * ng1 * siluf_(bf2f((u16)g1r[i])));
;       }
	global_store_short_d16_hi v[194:195], v22, off
	v_mul_f32_e32 v22, v23, v193
	v_lshlrev_b32_e32 v23, 16, v191
	v_mul_f32_e32 v191, 0xbfb8aa3b, v23
	v_exp_f32_e32 v191, v191
	v_mul_f32_e32 v22, v127, v22
	v_add_f32_e32 v191, 1.0, v191
	s_nop 0
	v_rcp_f32_e32 v192, v191
	s_nop 0
	v_mul_f32_e32 v23, v23, v192
	v_mul_f32_e32 v22, v23, v22
	v_bfe_u32 v23, v22, 16, 1
	v_add3_u32 v22, v22, v23, s21
	global_store_short_d16_hi v[194:195], v22, off offset:128
	v_lshlrev_b32_e32 v22, 16, v167
	v_lshlrev_b32_e32 v23, 16, v190
	v_lshlrev_b32_e32 v190, 16, v165
	v_lshlrev_b32_e32 v191, 16, v166
	v_pk_add_f32 v[22:23], v[22:23], v[190:191]
	v_mul_f32_e32 v190, 0xbfb8aa3b, v164
	v_pk_mul_f32 v[166:167], v[22:23], v[22:23]
	v_exp_f32_e32 v190, v190
	v_add_f32_e32 v165, v166, v167
	v_mov_b32_e32 v166, v129
	v_add_f32_e32 v190, 1.0, v190
	v_add_f32_dpp v165, v165, v165 quad_perm:[1,0,3,2] row_mask:0xf bank_mask:0xf bound_ctrl:1
	s_nop 0
	s_nop 0
	v_add_f32_dpp v165, v165, v165 quad_perm:[2,3,0,1] row_mask:0xf bank_mask:0xf bound_ctrl:1
	s_nop 0
	s_nop 0
	v_add_f32_dpp v165, v165, v165 row_half_mirror row_mask:0xf bank_mask:0xf bound_ctrl:1
	s_nop 0
	s_nop 0
	v_add_f32_dpp v165, v165, v165 row_mirror row_mask:0xf bank_mask:0xf bound_ctrl:1
	s_nop 0
	s_nop 0
	v_mov_b32_dpp v166, v165 row_bcast:15 row_mask:0xa bank_mask:0xf
	v_add_f32_e32 v165, v165, v166
	v_mov_b32_e32 v166, v129
	s_nop 1
	v_mov_b32_dpp v166, v165 row_bcast:31 row_mask:0xc bank_mask:0xf
	v_add_f32_e32 v165, v165, v166
	s_nop 0
	v_readlane_b32 s20, v165, 63
	s_nop 1
	v_fma_f32 v165, s20, v182, v169
	v_cmp_gt_f32_e32 vcc, s33, v165
	v_mul_f32_e32 v166, 0x4b800000, v165
	s_nop 0
	v_cndmask_b32_e32 v165, v165, v166, vcc
	v_rsq_f32_e32 v165, v165
	s_nop 0
	v_mul_f32_e32 v166, 0x45800000, v165
	v_cndmask_b32_e32 v165, v165, v166, vcc
	v_mul_f32_e32 v22, v22, v165
	v_mul_f32_e32 v22, v126, v22
	v_rcp_f32_e32 v191, v190
	s_nop 0
	v_mul_f32_e32 v164, v164, v191
	v_mul_f32_e32 v22, v164, v22
	v_bfe_u32 v164, v22, 16, 1
	v_lshl_add_u64 v[166:167], v[12:13], 0, s[42:43]
	v_add3_u32 v22, v22, v164, s21
	global_store_short_d16_hi v[166:167], v22, off
	v_mul_f32_e32 v22, v23, v165
	v_lshlrev_b32_e32 v23, 16, v163
	v_mul_f32_e32 v163, 0xbfb8aa3b, v23
	v_exp_f32_e32 v163, v163
	v_mul_f32_e32 v22, v127, v22
	v_add_f32_e32 v163, 1.0, v163
	s_nop 0
	v_rcp_f32_e32 v164, v163
	s_nop 0
	v_mul_f32_e32 v23, v23, v164
	v_mul_f32_e32 v22, v23, v22
	v_bfe_u32 v23, v22, 16, 1
	v_add3_u32 v22, v22, v23, s21
	global_store_short_d16_hi v[166:167], v22, off offset:128
	v_lshlrev_b32_e32 v22, 16, v161
	v_lshlrev_b32_e32 v23, 16, v162
	v_lshlrev_b32_e32 v162, 16, v159
	v_lshlrev_b32_e32 v163, 16, v160
	v_pk_add_f32 v[22:23], v[22:23], v[162:163]
	v_mul_f32_e32 v162, 0xbfb8aa3b, v158
	v_pk_mul_f32 v[160:161], v[22:23], v[22:23]
	v_exp_f32_e32 v162, v162
	v_add_f32_e32 v159, v160, v161
	v_mov_b32_e32 v160, v129
	v_add_f32_e32 v162, 1.0, v162
	v_add_f32_dpp v159, v159, v159 quad_perm:[1,0,3,2] row_mask:0xf bank_mask:0xf bound_ctrl:1
	s_nop 1
	v_add_f32_dpp v159, v159, v159 quad_perm:[2,3,0,1] row_mask:0xf bank_mask:0xf bound_ctrl:1
	s_nop 1
	v_add_f32_dpp v159, v159, v159 row_half_mirror row_mask:0xf bank_mask:0xf bound_ctrl:1
	s_nop 1
	v_add_f32_dpp v159, v159, v159 row_mirror row_mask:0xf bank_mask:0xf bound_ctrl:1
	s_nop 1
	v_mov_b32_dpp v160, v159 row_bcast:15 row_mask:0xa bank_mask:0xf
	v_add_f32_e32 v159, v159, v160
	v_mov_b32_e32 v160, v129
	s_nop 1
	v_mov_b32_dpp v160, v159 row_bcast:31 row_mask:0xc bank_mask:0xf
	v_add_f32_e32 v159, v159, v160
	s_nop 0
	v_readlane_b32 s20, v159, 63
	s_nop 1
	v_fma_f32 v159, s20, v182, v169
	v_cmp_gt_f32_e32 vcc, s33, v159
	v_mul_f32_e32 v160, 0x4b800000, v159
	s_nop 0
	v_cndmask_b32_e32 v159, v159, v160, vcc
	v_rsq_f32_e32 v159, v159
	s_nop 0
	v_mul_f32_e32 v160, 0x45800000, v159
	v_cndmask_b32_e32 v159, v159, v160, vcc
	v_lshl_add_u64 v[160:161], v[12:13], 0, s[2:3]
	v_mul_f32_e32 v22, v22, v159
	v_mul_f32_e32 v22, v126, v22
	v_rcp_f32_e32 v163, v162
	s_nop 0
	v_mul_f32_e32 v158, v158, v163
	v_mul_f32_e32 v22, v158, v22
	v_bfe_u32 v158, v22, 16, 1
	v_add3_u32 v22, v22, v158, s21
	global_store_short_d16_hi v[160:161], v22, off
	v_mul_f32_e32 v22, v23, v159
	v_lshlrev_b32_e32 v23, 16, v157
	v_mul_f32_e32 v157, 0xbfb8aa3b, v23
	v_exp_f32_e32 v157, v157
	v_mul_f32_e32 v22, v127, v22
	v_add_f32_e32 v157, 1.0, v157
	s_nop 0
; __device__ __forceinline__ float bf2f(u16 v) { return __uint_as_float(((unsigned)v) << 16); }
; __device__ __forceinline__ float siluf_(float x) { return x / (1.f + __expf(-x)); }
; __device__ void phase_combine(const P& p, int l, int ntok, float* lds) {
;     ...
;   for (int tile = blockIdx.x; tile < ntok / 16; tile += gridDim.x) {
;     ...
;       for (int i = 0; i < 4; ++i) {
;         int row = r0 + i0 + i;
;         float o0 = bf2f((u16)a0[i]) + bf2f((u16)a1[i]), o1 = bf2f((u16)a2[i]) + bf2f((u16)a3[i]);
;         float ss = wave_sum_b(o0 * o0 + o1 * o1);
;         float rstd = rsqrtf(ss * (1.f / 128.f) + 1e-6f);
;         u16* dst = p.nbuf + (size_t)row * D + mixer * 512 + hh * 128 + lane;
;         dst[0] = f2bf(o0 * rstd * ng0 * siluf_(bf2f((u16)g0r[i])));
;         dst[64] = f2bf(o1 * rstd * ng1 * siluf_(bf2f((u16)g1r[i])));
;       }
; #pragma unroll
;       for (int i = 0; i < 4; ++i) {
;         int tr = (tb + i0 + i) & (RL - 1);
;         float up = tr != 0 ? bf2f((u16)ucc[i]) * bf2f((u16)uch[i]) : 0.f;
;         float uc = bf2f((u16)ucc[i + 1]) * bf2f((u16)uch[i + 1]);
;         float un = tr != RL - 1 ? bf2f((u16)ucc[i + 2]) * bf2f((u16)uch[i + 2]) : 0.f;
;         float cv = scw0 * up + scw1 * uc + scw2 * un;
;         p.nbuf[(size_t)(r0 + i0 + i) * D + 1024 + tid] = f2bf(bf2f((u16)cbr[i]) * cv);
;       }
	v_rcp_f32_e32 v158, v157
	s_nop 0
	v_mul_f32_e32 v23, v23, v158
	v_mul_f32_e32 v22, v23, v22
	v_bfe_u32 v23, v22, 16, 1
	v_add3_u32 v22, v22, v23, s21
	global_store_short_d16_hi v[160:161], v22, off offset:128
	v_lshlrev_b32_e32 v22, 16, v155
	v_lshlrev_b32_e32 v23, 16, v156
	v_lshlrev_b32_e32 v156, 16, v153
	v_lshlrev_b32_e32 v157, 16, v154
	v_pk_add_f32 v[22:23], v[22:23], v[156:157]
	v_mul_f32_e32 v156, 0xbfb8aa3b, v152
	v_pk_mul_f32 v[154:155], v[22:23], v[22:23]
	v_exp_f32_e32 v156, v156
	v_add_f32_e32 v153, v154, v155
	v_mov_b32_e32 v154, v129
	v_add_f32_e32 v156, 1.0, v156
	v_add_f32_dpp v153, v153, v153 quad_perm:[1,0,3,2] row_mask:0xf bank_mask:0xf bound_ctrl:1
	s_nop 1
	v_add_f32_dpp v153, v153, v153 quad_perm:[2,3,0,1] row_mask:0xf bank_mask:0xf bound_ctrl:1
	s_nop 1
	v_add_f32_dpp v153, v153, v153 row_half_mirror row_mask:0xf bank_mask:0xf bound_ctrl:1
	s_nop 1
	v_add_f32_dpp v153, v153, v153 row_mirror row_mask:0xf bank_mask:0xf bound_ctrl:1
	s_nop 1
	v_mov_b32_dpp v154, v153 row_bcast:15 row_mask:0xa bank_mask:0xf
	v_add_f32_e32 v153, v153, v154
	v_mov_b32_e32 v154, v129
	s_nop 1
	v_mov_b32_dpp v154, v153 row_bcast:31 row_mask:0xc bank_mask:0xf
	v_add_f32_e32 v153, v153, v154
	s_nop 0
	v_readlane_b32 s2, v153, 63
	s_nop 1
	v_fma_f32 v153, s2, v182, v169
	v_cmp_gt_f32_e32 vcc, s33, v153
	v_mul_f32_e32 v154, 0x4b800000, v153
	s_nop 0
	v_cndmask_b32_e32 v153, v153, v154, vcc
	v_rsq_f32_e32 v153, v153
	s_nop 0
	v_mul_f32_e32 v154, 0x45800000, v153
	v_cndmask_b32_e32 v153, v153, v154, vcc
	v_lshl_add_u64 v[154:155], v[12:13], 0, s[0:1]
	v_mul_f32_e32 v22, v22, v153
	v_mul_f32_e32 v22, v126, v22
	v_rcp_f32_e32 v157, v156
	s_nop 0
	v_mul_f32_e32 v152, v152, v157
	v_mul_f32_e32 v22, v152, v22
	v_bfe_u32 v152, v22, 16, 1
	v_add3_u32 v22, v22, v152, s21
	global_store_short_d16_hi v[154:155], v22, off
	v_mul_f32_e32 v22, v23, v153
	v_lshlrev_b32_e32 v23, 16, v149
	v_mul_f32_e32 v149, 0xbfb8aa3b, v23
	v_exp_f32_e32 v149, v149
	v_mul_f32_e32 v22, v127, v22
	v_add_f32_e32 v149, 1.0, v149
	s_and_b32 s0, s46, s58
	s_cmp_lg_u32 s0, 0
	v_rcp_f32_e32 v152, v149
	s_nop 0
	v_mul_f32_e32 v23, v23, v152
	v_mul_f32_e32 v22, v23, v22
	v_bfe_u32 v23, v22, 16, 1
	v_add3_u32 v22, v22, v23, s21
	global_store_short_d16_hi v[154:155], v22, off offset:128
	v_lshlrev_b32_e32 v22, 16, v139
	v_lshlrev_b32_e32 v23, 16, v140
	v_mul_f32_e32 v22, v22, v23
	s_cselect_b64 vcc, -1, 0
	v_cndmask_b32_e32 v22, 0, v22, vcc
	v_lshlrev_b32_e32 v23, 16, v147
	v_lshlrev_b32_e32 v139, 16, v148
	v_mul_f32_e32 v23, v23, v139
	v_lshlrev_b32_e32 v139, 16, v150
	v_lshlrev_b32_e32 v140, 16, v151
	v_mul_f32_e32 v22, v123, v22
	v_mul_f32_e32 v139, v139, v140
	v_fmac_f32_e32 v22, v124, v23
	v_fmac_f32_e32 v22, v125, v139
	v_mul_f32_e32 v22, v22, v138
	v_bfe_u32 v138, v22, 16, 1
	v_add3_u32 v22, v22, v138, s21
	global_store_short_d16_hi v[18:19], v22, off offset:2048
	v_lshlrev_b32_e32 v18, 16, v145
	v_lshlrev_b32_e32 v19, 16, v146
	v_mul_f32_e32 v18, v18, v19
	v_mul_f32_e32 v19, v124, v139
	v_fmac_f32_e32 v19, v123, v23
	v_fmac_f32_e32 v19, v125, v18
	v_lshlrev_b32_e32 v22, 16, v137
	v_mul_f32_e32 v19, v19, v22
	v_bfe_u32 v22, v19, 16, 1
	v_add3_u32 v19, v19, v22, s21
	global_store_short_d16_hi v[20:21], v19, off offset:2048
	v_lshlrev_b32_e32 v19, 16, v143
	v_lshlrev_b32_e32 v20, 16, v144
	v_mul_f32_e32 v19, v19, v20
	v_mul_f32_e32 v20, v124, v18
	v_fmac_f32_e32 v20, v123, v139
	v_fmac_f32_e32 v20, v125, v19
	v_lshlrev_b32_e32 v21, 16, v136
	v_mul_f32_e32 v20, v20, v21
	v_bfe_u32 v21, v20, 16, 1
	v_add3_u32 v20, v20, v21, s21
	s_and_b32 s0, s36, s58
	global_store_short_d16_hi v[2:3], v20, off offset:2048
	v_lshlrev_b32_e32 v2, 16, v141
	v_lshlrev_b32_e32 v3, 16, v142
	s_cmp_lg_u32 s0, s58
	v_mul_f32_e32 v2, v2, v3
	s_cselect_b64 vcc, -1, 0
	v_mul_f32_e32 v3, v124, v19
	v_cndmask_b32_e32 v2, 0, v2, vcc
	v_fmac_f32_e32 v3, v123, v18
	v_fmac_f32_e32 v3, v125, v2
	v_lshlrev_b32_e32 v2, 16, v135
	v_mul_f32_e32 v2, v3, v2
	v_bfe_u32 v3, v2, 16, 1
	s_add_i32 s0, s60, 4
	v_add3_u32 v2, v2, v3, s21
	s_cmp_gt_u32 s60, 11
	s_mov_b32 s60, s0
	global_store_short_d16_hi v[0:1], v2, off offset:2048
	s_cbranch_scc0 .LBB0_94
	v_readlane_b32 s0, v240, 4
	v_readlane_b32 s1, v240, 5
	s_load_dword s0, s[0:1], 0x0
	s_movk_i32 s33, 0x3600
	s_waitcnt lgkmcnt(0)
	s_add_i32 s55, s0, s55
	s_cmp_ge_i32 s55, s72
	s_cbranch_scc0 .LBB0_90
